# stack9 + P0 rms rows handled in pairs (second row's x loads in flight while the first row is reduced and stored)
# speedup vs baseline: 1.0043x; 1.0043x over previous
; #define GAS __attribute__((address_space(1)))
; __device__ __forceinline__ unsigned pk2(float lo, float hi) { const f32x2pk v = {lo, hi}; return __builtin_bit_cast(unsigned, __builtin_convertvector(v, bf16x2pk)); }
; __device__ __forceinline__ void rms_row_to_bf16(const float* xrow, const float* g, bf16* orow, int lane) {
;     const GAS f32x4* xr = (const GAS f32x4*)xrow + lane; const GAS f32x4* gr = (const GAS f32x4*)g + lane;
;     f32x4 v[4]; float s = 0.f;
; #pragma unroll
;     for (int j = 0; j < 4; ++j) { v[j] = xr[64 * j]; s += (v[j].x * v[j].x + v[j].y * v[j].y) + (v[j].z * v[j].z + v[j].w * v[j].w); }
;     const float rinv = 1.f / sqrtf(wave_sum(s) * (1.f / DMODEL) + EPS);
;     GAS unsigned long long* o8 = (GAS unsigned long long*)orow + lane;
; #pragma unroll
;     for (int j = 0; j < 4; ++j) { const f32x4 gg = gr[64 * j]; const f32x4 y = v[j] * rinv * gg;
;         o8[64 * j] = (unsigned long long)pk2(y.x, y.y) | ((unsigned long long)pk2(y.z, y.w) << 32); }
; }
; __global__ void __launch_bounds__(512, 2) mk_fwd(Args a) {
;     ...
;         for (int m = gw; m < MTOT + MMEM; m += NGW) {
;             if (m < MP) rms_row_to_bf16(INF(I_XP) + (size_t)m * DMODEL, INF(I_LN1), (bf16*)(ws + WS_XN1) + (size_t)m * DMODEL, lane);
.LBB0_130:
	s_andn2_b64 vcc, exec, s[0:1]
	s_cbranch_vccnz .LBB0_123
	v_readlane_b32 s0, v255, 3
	s_add_i32 s1, s3, s0
	s_cmpk_gt_i32 s1, 0x3fff
	s_cbranch_scc1 .Lmy_rms_single
	global_load_dwordx4 v[2:5], v[20:21], off offset:-3072
	global_load_dwordx4 v[26:29], v[20:21], off offset:-2048
	global_load_dwordx4 v[30:33], v[20:21], off offset:-1024
	global_load_dwordx4 v[34:37], v[20:21], off
	global_load_dwordx4 v[38:41], v[14:15], off
	global_load_dwordx4 v[130:133], v[14:15], off offset:1024
	global_load_dwordx4 v[134:137], v[14:15], off offset:2048
	global_load_dwordx4 v[138:141], v[14:15], off offset:3072
	v_lshl_add_u64 v[158:159], v[20:21], 0, s[8:9]
	v_lshl_add_u64 v[160:161], v[18:19], 0, s[6:7]
	global_load_dwordx4 v[142:145], v[158:159], off offset:-3072
	global_load_dwordx4 v[146:149], v[158:159], off offset:-2048
	global_load_dwordx4 v[150:153], v[158:159], off offset:-1024
	global_load_dwordx4 v[154:157], v[158:159], off
	v_mov_b32_e32 v22, 0
	v_mov_b32_e32 v23, 0
	s_waitcnt vmcnt(11)
	v_mul_f32_e32 v42, v3, v3
	v_mul_f32_e32 v43, v5, v5
	s_waitcnt vmcnt(10)
	v_mul_f32_e32 v44, v27, v27
	v_mul_f32_e32 v45, v29, v29
	s_waitcnt vmcnt(9)
	v_mul_f32_e32 v46, v31, v31
	v_mul_f32_e32 v47, v33, v33
	v_fmac_f32_e32 v42, v2, v2
	v_fmac_f32_e32 v43, v4, v4
	v_fmac_f32_e32 v44, v26, v26
	v_fmac_f32_e32 v45, v28, v28
	s_waitcnt vmcnt(8)
	v_mul_f32_e32 v48, v35, v35
	v_mul_f32_e32 v49, v37, v37
	v_fmac_f32_e32 v46, v30, v30
	v_fmac_f32_e32 v47, v32, v32
	v_add_f32_e32 v42, v42, v43
	v_add_f32_e32 v43, v44, v45
	v_fmac_f32_e32 v48, v34, v34
	v_fmac_f32_e32 v49, v36, v36
	v_add_f32_e32 v44, v46, v47
	v_add_f32_e32 v42, v42, v43
	v_add_f32_e32 v45, v48, v49
	v_add_f32_e32 v42, v42, v44
	v_add_f32_e32 v42, v42, v45
	s_nop 1
	v_add_f32_dpp v42, v42, v42 row_shr:1 row_mask:0xf bank_mask:0xf bound_ctrl:1
	s_nop 1
	v_add_f32_dpp v42, v42, v42 row_shr:2 row_mask:0xf bank_mask:0xf bound_ctrl:1
	s_nop 1
	v_add_f32_dpp v42, v42, v42 row_shr:4 row_mask:0xf bank_mask:0xf bound_ctrl:1
	s_nop 1
	v_add_f32_dpp v42, v42, v42 row_shr:8 row_mask:0xf bank_mask:0xf bound_ctrl:1
	s_nop 1
	v_mov_b32_dpp v22, v42 row_bcast:15 row_mask:0xa bank_mask:0xf
	v_add_f32_e32 v22, v42, v22
	s_nop 1
	v_mov_b32_dpp v23, v22 row_bcast:31 row_mask:0xc bank_mask:0xf
	v_add_f32_e32 v22, v22, v23
	s_nop 0
	v_readlane_b32 s0, v22, 63
	s_nop 1
	v_fma_f32 v22, s0, v25, v1
	v_mul_f32_e32 v23, 0x4f800000, v22
	v_cmp_gt_f32_e32 vcc, s13, v22
	s_nop 1
	v_cndmask_b32_e32 v22, v22, v23, vcc
	v_sqrt_f32_e32 v23, v22
	s_nop 0
	v_add_u32_e32 v42, -1, v23
	v_add_u32_e32 v43, 1, v23
	v_fma_f32 v44, -v42, v23, v22
	v_fma_f32 v45, -v43, v23, v22
	v_cmp_ge_f32_e64 s[0:1], 0, v44
	s_nop 1
	v_cndmask_b32_e64 v23, v23, v42, s[0:1]
	v_cmp_lt_f32_e64 s[0:1], 0, v45
	s_nop 1
	v_cndmask_b32_e64 v23, v23, v43, s[0:1]
	v_mul_f32_e32 v42, 0x37800000, v23
	v_cndmask_b32_e32 v23, v23, v42, vcc
	v_cmp_class_f32_e32 vcc, v22, v24
	s_nop 1
	v_cndmask_b32_e32 v22, v23, v22, vcc
	v_div_scale_f32 v23, s[0:1], v22, v22, 1.0
	v_rcp_f32_e32 v42, v23
	v_div_scale_f32 v43, vcc, 1.0, v22, 1.0
	v_fma_f32 v44, -v23, v42, 1.0
	v_fmac_f32_e32 v42, v44, v42
	v_mul_f32_e32 v44, v43, v42
	v_fma_f32 v45, -v23, v44, v43
	v_fmac_f32_e32 v44, v45, v42
	v_fma_f32 v23, -v23, v44, v43
	v_div_fmas_f32 v23, v23, v42, v44
	v_div_fixup_f32 v22, v23, v22, 1.0
	v_pk_mul_f32 v[2:3], v[2:3], v[22:23] op_sel_hi:[1,0]
	v_pk_mul_f32 v[4:5], v[4:5], v[22:23] op_sel_hi:[1,0]
	s_waitcnt vmcnt(7)
	v_pk_mul_f32 v[2:3], v[38:39], v[2:3]
	v_pk_mul_f32 v[4:5], v[40:41], v[4:5]
	v_cvt_pk_bf16_f32 v2, v2, v3
	v_cvt_pk_bf16_f32 v3, v4, v5
	global_store_dwordx2 v[18:19], v[2:3], off
	v_pk_mul_f32 v[26:27], v[26:27], v[22:23] op_sel_hi:[1,0]
	v_pk_mul_f32 v[28:29], v[28:29], v[22:23] op_sel_hi:[1,0]
	s_waitcnt vmcnt(7)
	v_pk_mul_f32 v[2:3], v[130:131], v[26:27]
	v_pk_mul_f32 v[4:5], v[132:133], v[28:29]
	v_cvt_pk_bf16_f32 v2, v2, v3
	v_cvt_pk_bf16_f32 v3, v4, v5
	global_store_dwordx2 v[18:19], v[2:3], off offset:512
	v_pk_mul_f32 v[26:27], v[30:31], v[22:23] op_sel_hi:[1,0]
	v_pk_mul_f32 v[28:29], v[32:33], v[22:23] op_sel_hi:[1,0]
	s_waitcnt vmcnt(7)
	v_pk_mul_f32 v[2:3], v[134:135], v[26:27]
	v_pk_mul_f32 v[4:5], v[136:137], v[28:29]
	v_cvt_pk_bf16_f32 v2, v2, v3
	v_cvt_pk_bf16_f32 v3, v4, v5
	global_store_dwordx2 v[18:19], v[2:3], off offset:1024
	v_pk_mul_f32 v[26:27], v[36:37], v[22:23] op_sel_hi:[1,0]
	v_pk_mul_f32 v[22:23], v[34:35], v[22:23] op_sel_hi:[1,0]
	s_waitcnt vmcnt(7)
	v_pk_mul_f32 v[4:5], v[26:27], v[140:141]
	v_pk_mul_f32 v[2:3], v[22:23], v[138:139]
	s_nop 0
	v_cvt_pk_bf16_f32 v2, v2, v3
	v_cvt_pk_bf16_f32 v3, v4, v5
	global_store_dwordx2 v[18:19], v[2:3], off offset:1536
	v_mov_b32_e32 v22, 0
	v_mov_b32_e32 v23, 0
	s_waitcnt vmcnt(7)
	v_mul_f32_e32 v42, v143, v143
	v_mul_f32_e32 v43, v145, v145
	s_waitcnt vmcnt(6)
	v_mul_f32_e32 v44, v147, v147
	v_mul_f32_e32 v45, v149, v149
	s_waitcnt vmcnt(5)
	v_mul_f32_e32 v46, v151, v151
	v_mul_f32_e32 v47, v153, v153
	v_fmac_f32_e32 v42, v142, v142
	v_fmac_f32_e32 v43, v144, v144
	v_fmac_f32_e32 v44, v146, v146
	v_fmac_f32_e32 v45, v148, v148
	s_waitcnt vmcnt(4)
; #define GAS __attribute__((address_space(1)))
; __device__ __forceinline__ unsigned pk2(float lo, float hi) { const f32x2pk v = {lo, hi}; return __builtin_bit_cast(unsigned, __builtin_convertvector(v, bf16x2pk)); }
; __device__ __forceinline__ void rms_row_to_bf16(const float* xrow, const float* g, bf16* orow, int lane) {
;     const GAS f32x4* xr = (const GAS f32x4*)xrow + lane; const GAS f32x4* gr = (const GAS f32x4*)g + lane;
;     f32x4 v[4]; float s = 0.f;
; #pragma unroll
;     for (int j = 0; j < 4; ++j) { v[j] = xr[64 * j]; s += (v[j].x * v[j].x + v[j].y * v[j].y) + (v[j].z * v[j].z + v[j].w * v[j].w); }
;     const float rinv = 1.f / sqrtf(wave_sum(s) * (1.f / DMODEL) + EPS);
;     GAS unsigned long long* o8 = (GAS unsigned long long*)orow + lane;
; #pragma unroll
;     for (int j = 0; j < 4; ++j) { const f32x4 gg = gr[64 * j]; const f32x4 y = v[j] * rinv * gg;
;         o8[64 * j] = (unsigned long long)pk2(y.x, y.y) | ((unsigned long long)pk2(y.z, y.w) << 32); }
; }
; __global__ void __launch_bounds__(512, 2) mk_fwd(Args a) {
;     ...
;         for (int m = gw; m < MTOT + MMEM; m += NGW) {
;             if (m < MP) rms_row_to_bf16(INF(I_XP) + (size_t)m * DMODEL, INF(I_LN1), (bf16*)(ws + WS_XN1) + (size_t)m * DMODEL, lane);
	v_mul_f32_e32 v48, v155, v155
	v_mul_f32_e32 v49, v157, v157
	v_fmac_f32_e32 v46, v150, v150
	v_fmac_f32_e32 v47, v152, v152
	v_add_f32_e32 v42, v42, v43
	v_add_f32_e32 v43, v44, v45
	v_fmac_f32_e32 v48, v154, v154
	v_fmac_f32_e32 v49, v156, v156
	v_add_f32_e32 v44, v46, v47
	v_add_f32_e32 v42, v42, v43
	v_add_f32_e32 v45, v48, v49
	v_add_f32_e32 v42, v42, v44
	v_add_f32_e32 v42, v42, v45
	s_nop 1
	v_add_f32_dpp v42, v42, v42 row_shr:1 row_mask:0xf bank_mask:0xf bound_ctrl:1
	s_nop 1
	v_add_f32_dpp v42, v42, v42 row_shr:2 row_mask:0xf bank_mask:0xf bound_ctrl:1
	s_nop 1
	v_add_f32_dpp v42, v42, v42 row_shr:4 row_mask:0xf bank_mask:0xf bound_ctrl:1
	s_nop 1
	v_add_f32_dpp v42, v42, v42 row_shr:8 row_mask:0xf bank_mask:0xf bound_ctrl:1
	s_nop 1
	v_mov_b32_dpp v22, v42 row_bcast:15 row_mask:0xa bank_mask:0xf
	v_add_f32_e32 v22, v42, v22
	s_nop 1
	v_mov_b32_dpp v23, v22 row_bcast:31 row_mask:0xc bank_mask:0xf
	v_add_f32_e32 v22, v22, v23
	s_nop 0
	v_readlane_b32 s0, v22, 63
	s_nop 1
	v_fma_f32 v22, s0, v25, v1
	v_mul_f32_e32 v23, 0x4f800000, v22
	v_cmp_gt_f32_e32 vcc, s13, v22
	s_nop 1
	v_cndmask_b32_e32 v22, v22, v23, vcc
	v_sqrt_f32_e32 v23, v22
	s_nop 0
	v_add_u32_e32 v42, -1, v23
	v_add_u32_e32 v43, 1, v23
	v_fma_f32 v44, -v42, v23, v22
	v_fma_f32 v45, -v43, v23, v22
	v_cmp_ge_f32_e64 s[0:1], 0, v44
	s_nop 1
	v_cndmask_b32_e64 v23, v23, v42, s[0:1]
	v_cmp_lt_f32_e64 s[0:1], 0, v45
	s_nop 1
	v_cndmask_b32_e64 v23, v23, v43, s[0:1]
	v_mul_f32_e32 v42, 0x37800000, v23
	v_cndmask_b32_e32 v23, v23, v42, vcc
	v_cmp_class_f32_e32 vcc, v22, v24
	s_nop 1
	v_cndmask_b32_e32 v22, v23, v22, vcc
	v_div_scale_f32 v23, s[0:1], v22, v22, 1.0
	v_rcp_f32_e32 v42, v23
	v_div_scale_f32 v43, vcc, 1.0, v22, 1.0
	v_fma_f32 v44, -v23, v42, 1.0
	v_fmac_f32_e32 v42, v44, v42
	v_mul_f32_e32 v44, v43, v42
	v_fma_f32 v45, -v23, v44, v43
	v_fmac_f32_e32 v44, v45, v42
	v_fma_f32 v23, -v23, v44, v43
	v_div_fmas_f32 v23, v23, v42, v44
	v_div_fixup_f32 v22, v23, v22, 1.0
	v_pk_mul_f32 v[142:143], v[142:143], v[22:23] op_sel_hi:[1,0]
	v_pk_mul_f32 v[144:145], v[144:145], v[22:23] op_sel_hi:[1,0]
	v_pk_mul_f32 v[142:143], v[38:39], v[142:143]
	v_pk_mul_f32 v[144:145], v[40:41], v[144:145]
	v_cvt_pk_bf16_f32 v142, v142, v143
	v_cvt_pk_bf16_f32 v143, v144, v145
	global_store_dwordx2 v[160:161], v[142:143], off
	v_pk_mul_f32 v[146:147], v[146:147], v[22:23] op_sel_hi:[1,0]
	v_pk_mul_f32 v[148:149], v[148:149], v[22:23] op_sel_hi:[1,0]
	v_pk_mul_f32 v[142:143], v[130:131], v[146:147]
	v_pk_mul_f32 v[144:145], v[132:133], v[148:149]
	v_cvt_pk_bf16_f32 v142, v142, v143
	v_cvt_pk_bf16_f32 v143, v144, v145
	global_store_dwordx2 v[160:161], v[142:143], off offset:512
	v_pk_mul_f32 v[146:147], v[150:151], v[22:23] op_sel_hi:[1,0]
	v_pk_mul_f32 v[148:149], v[152:153], v[22:23] op_sel_hi:[1,0]
	v_pk_mul_f32 v[142:143], v[134:135], v[146:147]
	v_pk_mul_f32 v[144:145], v[136:137], v[148:149]
	v_cvt_pk_bf16_f32 v142, v142, v143
	v_cvt_pk_bf16_f32 v143, v144, v145
	global_store_dwordx2 v[160:161], v[142:143], off offset:1024
	v_pk_mul_f32 v[146:147], v[156:157], v[22:23] op_sel_hi:[1,0]
	v_pk_mul_f32 v[22:23], v[154:155], v[22:23] op_sel_hi:[1,0]
	v_pk_mul_f32 v[144:145], v[146:147], v[140:141]
	v_pk_mul_f32 v[142:143], v[22:23], v[138:139]
	s_nop 0
	v_cvt_pk_bf16_f32 v142, v142, v143
	v_cvt_pk_bf16_f32 v143, v144, v145
	global_store_dwordx2 v[160:161], v[142:143], off offset:1536
	v_readlane_b32 s0, v255, 3
	s_lshl_b32 s0, s0, 1
	s_add_i32 s2, s2, s0
	s_add_i32 s4, s4, s12
	s_add_i32 s4, s4, s12
	s_add_i32 s0, s2, 0x4200
	v_lshl_add_u64 v[18:19], v[160:161], 0, s[6:7]
	v_lshl_add_u64 v[20:21], v[158:159], 0, s[8:9]
	s_cmpk_gt_i32 s0, 0x45ff
	v_readlane_b32 s1, v255, 4
	s_cbranch_scc1 .LBB0_132
	s_branch .LBB0_124
; #define GAS __attribute__((address_space(1)))
; __device__ __forceinline__ unsigned pk2(float lo, float hi) { const f32x2pk v = {lo, hi}; return __builtin_bit_cast(unsigned, __builtin_convertvector(v, bf16x2pk)); }
; __device__ __forceinline__ void rms_row_to_bf16(const float* xrow, const float* g, bf16* orow, int lane) {
;     const GAS f32x4* xr = (const GAS f32x4*)xrow + lane; const GAS f32x4* gr = (const GAS f32x4*)g + lane;
;     f32x4 v[4]; float s = 0.f;
; #pragma unroll
;     for (int j = 0; j < 4; ++j) { v[j] = xr[64 * j]; s += (v[j].x * v[j].x + v[j].y * v[j].y) + (v[j].z * v[j].z + v[j].w * v[j].w); }
;     const float rinv = 1.f / sqrtf(wave_sum(s) * (1.f / DMODEL) + EPS);
;     GAS unsigned long long* o8 = (GAS unsigned long long*)orow + lane;
; #pragma unroll
;     for (int j = 0; j < 4; ++j) { const f32x4 gg = gr[64 * j]; const f32x4 y = v[j] * rinv * gg;
;         o8[64 * j] = (unsigned long long)pk2(y.x, y.y) | ((unsigned long long)pk2(y.z, y.w) << 32); }
; }
; __global__ void __launch_bounds__(512, 2) mk_fwd(Args a) {
;     ...
;         for (int m = gw; m < MTOT + MMEM; m += NGW) {
;             if (m < MP) rms_row_to_bf16(INF(I_XP) + (size_t)m * DMODEL, INF(I_LN1), (bf16*)(ws + WS_XN1) + (size_t)m * DMODEL, lane);
;             else if (m < MTOT) rms_row_to_bf16(INF(I_XS) + (size_t)(m - MP) * DMODEL, INF(I_LN1), (bf16*)(ws + WS_XN1) + (size_t)m * DMODEL, lane);
;             else rms_row_to_bf16(INF(I_MEM) + (size_t)(m - MTOT) * DMODEL, INF(I_MEMG), (bf16*)(ws + WS_MN) + (size_t)(m - MTOT) * DMODEL, lane);
;         }
.Lmy_rms_single:
	global_load_dwordx4 v[2:5], v[20:21], off offset:-3072
	global_load_dwordx4 v[26:29], v[20:21], off offset:-2048
	global_load_dwordx4 v[30:33], v[20:21], off offset:-1024
	global_load_dwordx4 v[34:37], v[20:21], off
	global_load_dwordx4 v[38:41], v[14:15], off
	global_load_dwordx4 v[130:133], v[14:15], off offset:1024
	global_load_dwordx4 v[134:137], v[14:15], off offset:2048
	global_load_dwordx4 v[138:141], v[14:15], off offset:3072
	v_mov_b32_e32 v22, 0
	v_mov_b32_e32 v23, 0
	s_waitcnt vmcnt(7)
	v_mul_f32_e32 v42, v3, v3
	v_mul_f32_e32 v43, v5, v5
	s_waitcnt vmcnt(6)
	v_mul_f32_e32 v44, v27, v27
	v_mul_f32_e32 v45, v29, v29
	s_waitcnt vmcnt(5)
	v_mul_f32_e32 v46, v31, v31
	v_mul_f32_e32 v47, v33, v33
	v_fmac_f32_e32 v42, v2, v2
	v_fmac_f32_e32 v43, v4, v4
	v_fmac_f32_e32 v44, v26, v26
	v_fmac_f32_e32 v45, v28, v28
	s_waitcnt vmcnt(4)
	v_mul_f32_e32 v48, v35, v35
	v_mul_f32_e32 v49, v37, v37
	v_fmac_f32_e32 v46, v30, v30
	v_fmac_f32_e32 v47, v32, v32
	v_add_f32_e32 v42, v42, v43
	v_add_f32_e32 v43, v44, v45
	v_fmac_f32_e32 v48, v34, v34
	v_fmac_f32_e32 v49, v36, v36
	v_add_f32_e32 v44, v46, v47
	v_add_f32_e32 v42, v42, v43
	v_add_f32_e32 v45, v48, v49
	v_add_f32_e32 v42, v42, v44
	v_add_f32_e32 v42, v42, v45
	s_nop 1
	v_add_f32_dpp v42, v42, v42 row_shr:1 row_mask:0xf bank_mask:0xf bound_ctrl:1
	s_nop 1
	v_add_f32_dpp v42, v42, v42 row_shr:2 row_mask:0xf bank_mask:0xf bound_ctrl:1
	s_nop 1
	v_add_f32_dpp v42, v42, v42 row_shr:4 row_mask:0xf bank_mask:0xf bound_ctrl:1
	s_nop 1
	v_add_f32_dpp v42, v42, v42 row_shr:8 row_mask:0xf bank_mask:0xf bound_ctrl:1
	s_nop 1
	v_mov_b32_dpp v22, v42 row_bcast:15 row_mask:0xa bank_mask:0xf
	v_add_f32_e32 v22, v42, v22
	s_nop 1
	v_mov_b32_dpp v23, v22 row_bcast:31 row_mask:0xc bank_mask:0xf
	v_add_f32_e32 v22, v22, v23
	s_nop 0
	v_readlane_b32 s0, v22, 63
	s_nop 1
	v_fma_f32 v22, s0, v25, v1
	v_mul_f32_e32 v23, 0x4f800000, v22
	v_cmp_gt_f32_e32 vcc, s13, v22
	s_nop 1
	v_cndmask_b32_e32 v22, v22, v23, vcc
	v_sqrt_f32_e32 v23, v22
	s_nop 0
	v_add_u32_e32 v42, -1, v23
	v_add_u32_e32 v43, 1, v23
	v_fma_f32 v44, -v42, v23, v22
	v_fma_f32 v45, -v43, v23, v22
	v_cmp_ge_f32_e64 s[0:1], 0, v44
	s_nop 1
	v_cndmask_b32_e64 v23, v23, v42, s[0:1]
	v_cmp_lt_f32_e64 s[0:1], 0, v45
	s_nop 1
	v_cndmask_b32_e64 v23, v23, v43, s[0:1]
	v_mul_f32_e32 v42, 0x37800000, v23
	v_cndmask_b32_e32 v23, v23, v42, vcc
	v_cmp_class_f32_e32 vcc, v22, v24
	s_nop 1
	v_cndmask_b32_e32 v22, v23, v22, vcc
	v_div_scale_f32 v23, s[0:1], v22, v22, 1.0
	v_rcp_f32_e32 v42, v23
	v_div_scale_f32 v43, vcc, 1.0, v22, 1.0
	v_fma_f32 v44, -v23, v42, 1.0
	v_fmac_f32_e32 v42, v44, v42
	v_mul_f32_e32 v44, v43, v42
	v_fma_f32 v45, -v23, v44, v43
	v_fmac_f32_e32 v44, v45, v42
	v_fma_f32 v23, -v23, v44, v43
	v_div_fmas_f32 v23, v23, v42, v44
	v_div_fixup_f32 v22, v23, v22, 1.0
	v_pk_mul_f32 v[2:3], v[2:3], v[22:23] op_sel_hi:[1,0]
	v_pk_mul_f32 v[4:5], v[4:5], v[22:23] op_sel_hi:[1,0]
	s_waitcnt vmcnt(3)
	v_pk_mul_f32 v[2:3], v[38:39], v[2:3]
	v_pk_mul_f32 v[4:5], v[40:41], v[4:5]
	v_cvt_pk_bf16_f32 v2, v2, v3
	v_cvt_pk_bf16_f32 v3, v4, v5
	global_store_dwordx2 v[18:19], v[2:3], off
	v_pk_mul_f32 v[26:27], v[26:27], v[22:23] op_sel_hi:[1,0]
	v_pk_mul_f32 v[28:29], v[28:29], v[22:23] op_sel_hi:[1,0]
	s_waitcnt vmcnt(3)
	v_pk_mul_f32 v[2:3], v[130:131], v[26:27]
	v_pk_mul_f32 v[4:5], v[132:133], v[28:29]
	v_cvt_pk_bf16_f32 v2, v2, v3
	v_cvt_pk_bf16_f32 v3, v4, v5
	global_store_dwordx2 v[18:19], v[2:3], off offset:512
	v_pk_mul_f32 v[26:27], v[30:31], v[22:23] op_sel_hi:[1,0]
	v_pk_mul_f32 v[28:29], v[32:33], v[22:23] op_sel_hi:[1,0]
	s_waitcnt vmcnt(3)
	v_pk_mul_f32 v[2:3], v[134:135], v[26:27]
	v_pk_mul_f32 v[4:5], v[136:137], v[28:29]
	v_cvt_pk_bf16_f32 v2, v2, v3
	v_cvt_pk_bf16_f32 v3, v4, v5
	global_store_dwordx2 v[18:19], v[2:3], off offset:1024
	v_pk_mul_f32 v[26:27], v[36:37], v[22:23] op_sel_hi:[1,0]
	v_pk_mul_f32 v[22:23], v[34:35], v[22:23] op_sel_hi:[1,0]
	s_waitcnt vmcnt(3)
	v_pk_mul_f32 v[4:5], v[26:27], v[140:141]
	v_pk_mul_f32 v[2:3], v[22:23], v[138:139]
	v_mov_b64_e32 v[22:23], v[18:19]
	s_branch .LBB0_123
